# attention PV section (first unrolled key tile): V fragment LDS reads prefetched one-two fragments ahead into v242-v253 instead of serialized read-wait-mfma; on top of v50
# speedup vs baseline: 1.0087x; 1.0050x over previous
; #define MFMA16(a, b, c) __builtin_amdgcn_mfma_f32_16x16x32_bf16((a), (b), (c), 0, 0, 0)
; __device__ __forceinline__ void attn_unit(const WS& ws, int u, bool dry = false) {
;     ...
;       const float mnew = mrun[nt];
;       float ps = 0.f;
; #pragma unroll
;       for (int mt = 0; mt < 4; ++mt)
; #pragma unroll
;         for (int jj = 0; jj < 4; ++jj) { const float pv = __builtin_amdgcn_exp2f(s[mt][nt][jj] - mnew); s[mt][nt][jj] = pv; ps += pv; }
;       lsum[nt] += ps;
; #pragma unroll
;       for (int ks = 0; ks < 2; ++ks) {
;         u32x4 pk;
;         pk.x = cvt_pk_bf16(s[2 * ks][nt][0], s[2 * ks][nt][1]); pk.y = cvt_pk_bf16(s[2 * ks][nt][2], s[2 * ks][nt][3]);
;         pk.z = cvt_pk_bf16(s[2 * ks + 1][nt][0], s[2 * ks + 1][nt][1]); pk.w = cvt_pk_bf16(s[2 * ks + 1][nt][2], s[2 * ks + 1][nt][3]);
;         pf[nt][ks] = as_bf16x8(pk);
;       }
;     }
; #pragma unroll
;     for (int mt = 0; mt < 4; ++mt)
; #pragma unroll
;       for (int ks = 0; ks < 2; ++ks) {
;         const u32x2 lo = *(const u32x2*)(Vb + (16 * mt + lr) * 72 + 32 * ks + 4 * lq);
;         const u32x2 hi = *(const u32x2*)(Vb + (16 * mt + lr) * 72 + 32 * ks + 16 + 4 * lq);
;         const bf16x8 vf = as_bf16x8((u32x4){lo.x, lo.y, hi.x, hi.y});
;         oacc[mt][0] = MFMA16(vf, pf[0][ks], oacc[mt][0]);
;         oacc[mt][1] = MFMA16(vf, pf[1][ks], oacc[mt][1]);
;       }
;     stores(buf ^ 1, kregn, vregn);
;     __syncthreads();
.LBB0_869:
	v_sub_f32_e32 v98, v98, v202
	v_exp_f32_e32 v208, v98
	v_sub_f32_e32 v98, v99, v202
	v_exp_f32_e32 v209, v98
	v_sub_f32_e32 v98, v100, v202
	v_exp_f32_e32 v210, v98
	v_sub_f32_e32 v98, v101, v202
	v_exp_f32_e32 v211, v98
	v_sub_f32_e32 v98, v102, v202
	v_exp_f32_e32 v212, v98
	v_sub_f32_e32 v98, v103, v202
	v_sub_f32_e32 v114, v114, v203
	v_exp_f32_e32 v213, v98
	v_sub_f32_e32 v98, v104, v202
	v_exp_f32_e32 v227, v114
	v_sub_f32_e32 v114, v115, v203
	v_exp_f32_e32 v214, v98
	v_sub_f32_e32 v98, v105, v202
	v_exp_f32_e32 v228, v114
	v_sub_f32_e32 v114, v116, v203
	v_exp_f32_e32 v215, v98
	v_sub_f32_e32 v98, v110, v202
	v_exp_f32_e32 v229, v114
	v_sub_f32_e32 v114, v117, v203
	v_exp_f32_e32 v216, v98
	v_sub_f32_e32 v98, v111, v202
	v_exp_f32_e32 v230, v114
	v_sub_f32_e32 v114, v118, v203
	v_exp_f32_e32 v205, v98
	v_sub_f32_e32 v98, v112, v202
	v_exp_f32_e32 v231, v114
	v_sub_f32_e32 v114, v119, v203
	v_exp_f32_e32 v206, v98
	v_sub_f32_e32 v98, v113, v202
	v_add_u32_e32 v103, 0x6800, v184
	v_exp_f32_e32 v232, v114
	v_sub_f32_e32 v114, v120, v203
	v_exp_f32_e32 v207, v98
	ds_read2_b64 v[98:101], v103 offset1:4
	v_exp_f32_e32 v233, v114
	v_sub_f32_e32 v114, v121, v203
	v_exp_f32_e32 v234, v114
	v_sub_f32_e32 v114, v122, v203
	v_exp_f32_e32 v235, v114
	v_sub_f32_e32 v114, v123, v203
	v_exp_f32_e32 v204, v114
	v_sub_f32_e32 v114, v124, v203
	v_exp_f32_e32 v221, v114
	v_sub_f32_e32 v114, v125, v203
	v_sub_f32_e32 v102, v106, v202
	v_exp_f32_e32 v223, v114
	v_sub_f32_e32 v114, v126, v203
	v_exp_f32_e32 v219, v102
	v_sub_f32_e32 v102, v107, v202
	ds_read2_b64 v[110:113], v103 offset0:8 offset1:12
	v_exp_f32_e32 v225, v114
	v_sub_f32_e32 v114, v127, v203
	v_exp_f32_e32 v217, v102
	v_sub_f32_e32 v102, v108, v202
	v_exp_f32_e32 v222, v114
	v_sub_f32_e32 v114, v128, v203
	v_cvt_pk_bf16_f32 v118, v227, v228
	v_cvt_pk_bf16_f32 v119, v229, v230
	v_cvt_pk_bf16_f32 v120, v231, v232
	v_cvt_pk_bf16_f32 v121, v233, v234
	v_exp_f32_e32 v218, v102
	v_cvt_pk_bf16_f32 v102, v208, v209
	v_cvt_pk_bf16_f32 v103, v210, v211
	v_cvt_pk_bf16_f32 v104, v212, v213
	v_cvt_pk_bf16_f32 v105, v214, v215
	v_exp_f32_e32 v224, v114
	v_sub_f32_e32 v114, v129, v203
	s_waitcnt lgkmcnt(1)
	v_mfma_f32_16x16x32_bf16 v[94:97], v[98:101], v[118:121], v[94:97]
	v_exp_f32_e32 v226, v114
	v_cvt_pk_bf16_f32 v114, v235, v204
	v_cvt_pk_bf16_f32 v115, v221, v223
	v_mfma_f32_16x16x32_bf16 v[62:65], v[98:101], v[102:105], v[62:65]
	v_sub_f32_e32 v98, v109, v202
	v_exp_f32_e32 v220, v98
	v_cvt_pk_bf16_f32 v116, v225, v222
	v_cvt_pk_bf16_f32 v117, v224, v226
	v_cvt_pk_bf16_f32 v106, v216, v205
	v_cvt_pk_bf16_f32 v107, v206, v207
	v_cvt_pk_bf16_f32 v108, v219, v217
	v_cvt_pk_bf16_f32 v109, v218, v220
	v_add_u32_e32 v98, 0x7000, v184
	v_add_u32_e32 v254, 0x7800, v184
	v_add_u32_e32 v255, 0x8000, v184
	ds_read2_b64 v[242:245], v98 offset0:32 offset1:36
	ds_read2_b64 v[246:249], v98 offset0:40 offset1:44
	ds_read2_b64 v[250:253], v254 offset0:64 offset1:68
	s_waitcnt lgkmcnt(3)
	v_mfma_f32_16x16x32_bf16 v[130:133], v[110:113], v[114:117], v[94:97]
	s_min_i32 s6, s35, s37
	s_lshl_b32 s6, s6, 6
	s_ashr_i32 s7, s6, 31
	v_mfma_f32_16x16x32_bf16 v[94:97], v[110:113], v[106:109], v[62:65]
	s_lshl_b64 s[8:9], s[6:7], 1
	s_add_i32 s5, s5, 1
	s_cmp_lt_u32 s5, s34
	s_waitcnt lgkmcnt(2)
	v_mfma_f32_16x16x32_bf16 v[90:93], v[242:245], v[118:121], v[90:93]
	v_mfma_f32_16x16x32_bf16 v[46:49], v[242:245], v[102:105], v[46:49]
	ds_read2_b64 v[242:245], v254 offset0:72 offset1:76
	v_add_u32_e32 v98, 0x7800, v184
	s_waitcnt lgkmcnt(2)
	v_mfma_f32_16x16x32_bf16 v[134:137], v[246:249], v[114:117], v[90:93]
	v_mfma_f32_16x16x32_bf16 v[90:93], v[246:249], v[106:109], v[46:49]
	ds_read2_b64 v[246:249], v255 offset0:96 offset1:100
	s_nop 2
	s_waitcnt lgkmcnt(2)
	v_mfma_f32_16x16x32_bf16 v[62:65], v[250:253], v[118:121], v[74:77]
	v_mfma_f32_16x16x32_bf16 v[38:41], v[250:253], v[102:105], v[38:41]
	ds_read2_b64 v[250:253], v255 offset0:104 offset1:108
	s_waitcnt lgkmcnt(2)
	v_mfma_f32_16x16x32_bf16 v[138:141], v[242:245], v[114:117], v[62:65]
	s_nop 3
	v_add_u32_e32 v62, 0x8000, v184
	v_mfma_f32_16x16x32_bf16 v[98:101], v[242:245], v[106:109], v[38:41]
	s_nop 2
	s_waitcnt lgkmcnt(1)
	v_mfma_f32_16x16x32_bf16 v[46:49], v[246:249], v[118:121], v[66:69]
	v_mfma_f32_16x16x32_bf16 v[34:37], v[246:249], v[102:105], v[34:37]
	s_waitcnt vmcnt(9)
	ds_write_b128 v177, v[18:21] offset:13312
	s_waitcnt vmcnt(8)
	ds_write_b128 v178, v[26:29] offset:13312
	s_waitcnt vmcnt(7)
	ds_write_b128 v179, v[42:45] offset:13312
	s_waitcnt vmcnt(6)
	ds_write_b128 v180, v[70:73] offset:35840
	s_waitcnt vmcnt(5)
	ds_write_b128 v181, v[78:81] offset:35840
	s_waitcnt lgkmcnt(0)
	s_barrier
; #define MFMA16(a, b, c) __builtin_amdgcn_mfma_f32_16x16x32_bf16((a), (b), (c), 0, 0, 0)
; __device__ __forceinline__ void attn_unit(const WS& ws, int u, bool dry = false) {
;     ...
;     { const int kn = kt + 2 < nkt2 ? kt + 2 : nkt2 - 1; loadg(kn, kreg, vreg); }
;     const bf16_t* Kb = Kt + buf * 64 * 104;
;     const bf16_t* Vb = Vl + buf * 64 * 72;
;     f32x4 s[4][2];
; #pragma unroll
;     for (int mt = 0; mt < 4; ++mt) {
;       s[mt][0] = (f32x4){0.f, 0.f, 0.f, 0.f}; s[mt][1] = (f32x4){0.f, 0.f, 0.f, 0.f};
; #pragma unroll
;       for (int ks = 0; ks < 3; ++ks) {
;         const bf16x8 kf = *(const bf16x8*)(Kb + (16 * mt + lr) * 104 + 32 * ks + 8 * lq);
;         s[mt][0] = MFMA16(kf, xq[0][ks], s[mt][0]);
;         s[mt][1] = MFMA16(kf, xq[1][ks], s[mt][1]);
;       }
;     }
;     ...
;         const u32x2 lo = *(const u32x2*)(Vb + (16 * mt + lr) * 72 + 32 * ks + 4 * lq);
;         const u32x2 hi = *(const u32x2*)(Vb + (16 * mt + lr) * 72 + 32 * ks + 16 + 4 * lq);
;         const bf16x8 vf = as_bf16x8((u32x4){lo.x, lo.y, hi.x, hi.y});
;         oacc[mt][0] = MFMA16(vf, pf[0][ks], oacc[mt][0]);
;         oacc[mt][1] = MFMA16(vf, pf[1][ks], oacc[mt][1]);
;       }
;     stores(buf ^ 1, kregn, vregn);
;     __syncthreads();
	ds_read_b128 v[18:21], v183 offset:13312
	ds_read_b128 v[26:29], v183 offset:13376
	v_mfma_f32_16x16x32_bf16 v[106:109], v[250:253], v[106:109], v[34:37]
	v_add_u32_e32 v42, s6, v171
	v_min_i32_e32 v42, 0x80f, v42
	s_waitcnt lgkmcnt(1)
	v_mfma_f32_16x16x32_bf16 v[34:37], v[18:21], v[0:3], 0
	v_mfma_f32_16x16x32_bf16 v[18:21], v[18:21], v[14:17], 0
	v_mfma_f32_16x16x32_bf16 v[142:145], v[250:253], v[114:117], v[46:49]
	s_waitcnt lgkmcnt(0)
	v_mfma_f32_16x16x32_bf16 v[34:37], v[26:29], v[4:7], v[34:37]
	s_nop 0
	v_add_u32_e32 v46, s66, v42
	v_ashrrev_i32_e32 v47, 31, v46
	v_lshlrev_b64 v[48:49], 11, v[46:47]
	v_mfma_f32_16x16x32_bf16 v[18:21], v[26:29], v[8:11], v[18:21]
	ds_read_b128 v[26:29], v183 offset:13440
	ds_read_b128 v[38:41], v183 offset:16640
	ds_read_b128 v[42:45], v183 offset:16768
	v_lshlrev_b64 v[46:47], 6, v[46:47]
	s_waitcnt lgkmcnt(2)
	v_mfma_f32_16x16x32_bf16 v[126:129], v[26:29], v[22:25], v[34:37]
	v_lshl_add_u64 v[62:63], v[154:155], 0, v[48:49]
	ds_read_b128 v[74:77], v183 offset:23424
	v_mfma_f32_16x16x32_bf16 v[34:37], v[26:29], v[30:33], v[18:21]
	s_nop 2
	ds_read_b128 v[18:21], v183 offset:16704
	s_waitcnt lgkmcnt(3)
	v_mfma_f32_16x16x32_bf16 v[26:29], v[38:41], v[0:3], 0
	v_mfma_f32_16x16x32_bf16 v[38:41], v[38:41], v[14:17], 0
	s_waitcnt lgkmcnt(0)
	v_mfma_f32_16x16x32_bf16 v[26:29], v[18:21], v[4:7], v[26:29]
	v_mfma_f32_16x16x32_bf16 v[38:41], v[18:21], v[8:11], v[38:41]
	v_lshl_add_u64 v[18:19], v[152:153], 0, v[46:47]
	ds_read_b128 v[46:49], v183 offset:19968
	v_lshl_add_u64 v[18:19], v[18:19], 0, s[86:87]
	v_mfma_f32_16x16x32_bf16 v[122:125], v[42:45], v[22:25], v[26:29]
	v_cndmask_b32_e64 v18, v18, v62, s[38:39]
	v_cndmask_b32_e64 v19, v19, v63, s[38:39]
	global_load_dwordx4 v[18:21], v[18:19], off
	v_add_u32_e32 v26, s6, v172
	v_min_i32_e32 v62, 0x80f, v26
	ds_read_b128 v[26:29], v183 offset:20032
	v_add_u32_e32 v62, s66, v62
	v_ashrrev_i32_e32 v63, 31, v62
	v_lshlrev_b64 v[64:65], 11, v[62:63]
	v_lshl_add_u64 v[66:67], v[158:159], 0, v[64:65]
	v_lshlrev_b64 v[68:69], 6, v[62:63]
	ds_read_b128 v[62:65], v183 offset:20096
	v_mfma_f32_16x16x32_bf16 v[38:41], v[42:45], v[30:33], v[38:41]
	v_lshl_add_u64 v[68:69], v[156:157], 0, v[68:69]
	v_lshl_add_u64 v[68:69], v[68:69], 0, s[86:87]
	v_cndmask_b32_e64 v67, v69, v67, s[40:41]
	s_waitcnt lgkmcnt(2)
	v_mfma_f32_16x16x32_bf16 v[42:45], v[46:49], v[0:3], 0
	v_cndmask_b32_e64 v66, v68, v66, s[40:41]
	v_mfma_f32_16x16x32_bf16 v[46:49], v[46:49], v[14:17], 0
	s_waitcnt lgkmcnt(1)
	v_mfma_f32_16x16x32_bf16 v[42:45], v[26:29], v[4:7], v[42:45]
	v_mfma_f32_16x16x32_bf16 v[46:49], v[26:29], v[8:11], v[46:49]
	global_load_dwordx4 v[26:29], v[66:67], off
	ds_read_b128 v[66:69], v183 offset:23296
	s_waitcnt lgkmcnt(1)
	v_mfma_f32_16x16x32_bf16 v[118:121], v[62:65], v[22:25], v[42:45]
	v_mfma_f32_16x16x32_bf16 v[46:49], v[62:65], v[30:33], v[46:49]
	ds_read_b128 v[62:65], v183 offset:23360
	s_nop 0
	v_add_u32_e32 v42, s6, v173
	v_min_i32_e32 v42, 0x80f, v42
	v_add_u32_e32 v70, s66, v42
	s_waitcnt lgkmcnt(1)
	v_mfma_f32_16x16x32_bf16 v[42:45], v[66:69], v[0:3], 0
	v_ashrrev_i32_e32 v71, 31, v70
	v_lshlrev_b64 v[72:73], 11, v[70:71]
	v_lshlrev_b64 v[70:71], 6, v[70:71]
	v_lshl_add_u64 v[70:71], v[160:161], 0, v[70:71]
	v_mfma_f32_16x16x32_bf16 v[66:69], v[66:69], v[14:17], 0
	v_lshl_add_u64 v[78:79], v[162:163], 0, v[72:73]
	v_lshl_add_u64 v[80:81], v[70:71], 0, s[86:87]
	v_cndmask_b32_e64 v79, v81, v79, s[42:43]
	s_waitcnt lgkmcnt(0)
	v_mfma_f32_16x16x32_bf16 v[70:73], v[62:65], v[4:7], v[42:45]
	v_cndmask_b32_e64 v78, v80, v78, s[42:43]
	v_mfma_f32_16x16x32_bf16 v[62:65], v[62:65], v[8:11], v[66:69]
	s_nop 0
	global_load_dwordx4 v[42:45], v[78:79], off
	s_nop 0
	v_lshl_add_u64 v[66:67], v[148:149], 0, s[8:9]
	v_lshl_add_u64 v[68:69], v[150:151], 0, s[8:9]
	v_mfma_f32_16x16x32_bf16 v[114:117], v[74:77], v[22:25], v[70:73]
	s_nop 2
	global_load_dwordx4 v[70:73], v[66:67], off
	global_load_dwordx4 v[78:81], v[68:69], off
	v_mfma_f32_16x16x32_bf16 v[62:65], v[74:77], v[30:33], v[62:65]
	s_cbranch_scc1 .LBB0_871
; __device__ __forceinline__ void attn_unit(const WS& ws, int u, bool dry = false) {
;     ...
;     if (kt >= 2 * qb) {
; #pragma unroll
;       for (int mt = 0; mt < 4; ++mt)
; #pragma unroll
;         for (int nt = 0; nt < 2; ++nt)
; #pragma unroll
;           for (int jj = 0; jj < 4; ++jj) {
;             const int key = 64 * kt + 16 * mt + 4 * lq + jj;
;             if (key > qi[nt]) s[mt][nt][jj] = -INFINITY;
;           }
;     }
	v_add_u32_e32 v67, 64, v185
	v_mov_b32_e32 v66, s17
	v_cmp_gt_i32_e32 vcc, v67, v169
	v_cmp_lt_i32_e64 s[44:45], v67, v169
	v_add_u32_e32 v68, 0x42, v185
	v_cndmask_b32_e32 v66, v126, v66, vcc
	v_cndmask_b32_e64 v126, v66, v126, s[44:45]
	v_cndmask_b32_e64 v127, v194, v127, s[44:45]
	v_cmp_le_i32_e64 s[44:45], v68, v169
	v_add_u32_e32 v69, 0x43, v185
	v_mov_b32_e32 v66, s17
	v_cndmask_b32_e64 v128, v194, v128, s[44:45]
	v_cmp_le_i32_e64 s[44:45], v69, v169
	v_add_u32_e32 v74, 0x63, v185
	s_nop 0
	v_cndmask_b32_e64 v129, v194, v129, s[44:45]
	v_cmp_gt_i32_e64 s[44:45], v67, v13
	s_nop 1
	v_cndmask_b32_e64 v66, v34, v66, s[44:45]
	v_cmp_lt_i32_e64 s[44:45], v67, v13
	v_add_u32_e32 v67, 0x50, v185
	s_nop 0
	v_cndmask_b32_e64 v34, v66, v34, s[44:45]
	v_cndmask_b32_e64 v35, v194, v35, s[44:45]
	v_cmp_le_i32_e64 s[44:45], v68, v13
	v_mov_b32_e32 v66, s17
	v_add_u32_e32 v68, 0x52, v185
	v_cndmask_b32_e64 v36, v194, v36, s[44:45]
	v_cmp_le_i32_e64 s[44:45], v69, v13
	v_cndmask_b32_e32 v38, v38, v66, vcc
	v_add_u32_e32 v69, 0x53, v185
	v_cndmask_b32_e64 v37, v194, v37, s[44:45]
	v_cmp_gt_i32_e64 s[44:45], v67, v169
	v_add_u32_e32 v67, 0x51, v185
	v_cmp_le_i32_e32 vcc, v67, v13
	v_cndmask_b32_e64 v122, v122, v66, s[44:45]
	v_cmp_le_i32_e64 s[44:45], v67, v169
	v_cndmask_b32_e32 v39, v194, v39, vcc
	v_cmp_le_i32_e32 vcc, v68, v13
	v_add_u32_e32 v67, 0x60, v185
	v_cndmask_b32_e64 v123, v194, v123, s[44:45]
	v_cndmask_b32_e32 v40, v194, v40, vcc
	v_cmp_le_i32_e32 vcc, v69, v13
	v_cmp_le_i32_e64 s[44:45], v68, v169
	v_add_u32_e32 v68, 0x61, v185
	v_cndmask_b32_e32 v41, v194, v41, vcc
	v_cmp_gt_i32_e32 vcc, v67, v169
	v_cndmask_b32_e64 v124, v194, v124, s[44:45]
	v_cmp_le_i32_e64 s[44:45], v69, v169
	v_cndmask_b32_e32 v118, v118, v66, vcc
	v_cmp_le_i32_e32 vcc, v68, v169
	v_add_u32_e32 v69, 0x62, v185
	v_cndmask_b32_e64 v125, v194, v125, s[44:45]
	v_cndmask_b32_e32 v119, v194, v119, vcc
	v_cmp_le_i32_e32 vcc, v69, v169
	s_nop 1
	v_cndmask_b32_e32 v120, v194, v120, vcc
	v_cmp_le_i32_e32 vcc, v74, v169
	s_nop 1
	v_cndmask_b32_e32 v121, v194, v121, vcc
	v_cmp_gt_i32_e32 vcc, v67, v13
	v_add_u32_e32 v67, 0x70, v185
	s_nop 0
	v_cndmask_b32_e32 v46, v46, v66, vcc
	v_cmp_le_i32_e32 vcc, v68, v13
	v_add_u32_e32 v68, 0x71, v185
	s_nop 0
	v_cndmask_b32_e32 v47, v194, v47, vcc
	v_cmp_le_i32_e32 vcc, v69, v13
	v_add_u32_e32 v69, 0x72, v185
	s_nop 0
	v_cndmask_b32_e32 v48, v194, v48, vcc
	v_cmp_le_i32_e32 vcc, v74, v13
	v_add_u32_e32 v74, 0x73, v185
	s_nop 0
	v_cndmask_b32_e32 v49, v194, v49, vcc
	v_cmp_gt_i32_e32 vcc, v67, v169
	s_nop 1
	v_cndmask_b32_e32 v114, v114, v66, vcc
	v_cmp_le_i32_e32 vcc, v68, v169
	s_nop 1
	v_cndmask_b32_e32 v115, v194, v115, vcc
	v_cmp_le_i32_e32 vcc, v69, v169
	s_nop 1
	v_cndmask_b32_e32 v116, v194, v116, vcc
	v_cmp_le_i32_e32 vcc, v74, v169
	s_nop 1
	v_cndmask_b32_e32 v117, v194, v117, vcc
	v_cmp_gt_i32_e32 vcc, v67, v13
	s_nop 1
	v_cndmask_b32_e32 v62, v62, v66, vcc
	v_cmp_le_i32_e32 vcc, v68, v13
	s_nop 1
	v_cndmask_b32_e32 v63, v194, v63, vcc
	v_cmp_le_i32_e32 vcc, v69, v13
	s_nop 1
	v_cndmask_b32_e32 v64, v194, v64, vcc
	v_cmp_le_i32_e32 vcc, v74, v13
	s_nop 1
	v_cndmask_b32_e32 v65, v194, v65, vcc
